# hw_sum reduction steps xor 8/4/2/1 via DPP row_ror adds instead of ds_bpermute round trips (bitwise identical sums)
# speedup vs baseline: 1.0615x; 1.0615x over previous
; NI void prepD_row(const P& p, int l, int t0) {
;     ...
;     float nwv[6];
;     const float* nwp = (isq ? p.in[I_MQQK] : p.in[I_MKQK]) + l * 192 + ln;
; #pragma unroll
;     for (int j = 0; j < 6; ++j) nwv[j] = nwp[32 * j];
;     const float invf = exp2f(-(float)(ln & 15) * (13.287712379549449f / 16.f));
; #pragma unroll
;     for (int rr = 0; rr < RBD; ++rr) {
;       const int t = t0 + rr;
;       const float rstd_in = rsqrtf(hw_sum(ssi[rr]) * (isq ? (1.f / 384.f) : (1.f / 256.f)) + EPS);
;       if (task < 8) {
;         const int nsc = isq ? 6 : 4;
; #pragma unroll
;         for (int j = 0; j < 6; ++j) if (j < nsc) x[rr][j] *= rstd_in;
;         float ss = 0.f;
; #pragma unroll
;         for (int j = 0; j < 6; ++j) ss += x[rr][j] * x[rr][j];
;         const float rstd = rsqrtf(hw_sum(ss) * (1.f / 192.f) + EPS);
; #pragma unroll
;         for (int j = 0; j < 6; ++j) x[rr][j] = x[rr][j] * rstd * nwv[j];
;         if (lat) {
;           const int tt = t - NCTX, rpos = tt >> 6, cpos = tt & 63;
;           float sn, c;
;           {
;             sincos_rev((float)rpos * invf, sn, c);
;             const float other = __shfl_xor(x[rr][4], 16);
;             x[rr][4] = (ln < 16) ? (x[rr][4] * c - other * sn) : (other * sn + x[rr][4] * c);
.LBB0_193:
	s_or_b64 exec, exec, s[18:19]
	v_readlane_b32 s40, v252, 4
	v_readlane_b32 s45, v252, 9
	v_readlane_b32 s47, v252, 11
	global_load_ushort v89, v[102:103], off
	global_load_ushort v122, v[102:103], off offset:64
	global_load_ushort v123, v[102:103], off offset:128
	s_nop 0
	global_load_ushort v102, v[102:103], off offset:192
	s_nop 0
	global_load_ushort v120, v[100:101], off
	global_load_ushort v117, v[98:99], off
	global_load_ushort v118, v[92:93], off
	global_load_ushort v119, v[104:105], off
	v_readlane_b32 s44, v252, 8
	v_readlane_b32 s46, v252, 10
	v_mov_b32_e32 v92, s47
	v_mov_b32_e32 v93, s45
	v_cndmask_b32_e64 v93, v92, v93, s[22:23]
	v_mov_b32_e32 v92, s46
	v_mov_b32_e32 v98, s44
	v_cndmask_b32_e64 v92, v92, v98, s[22:23]
	v_lshl_add_u64 v[92:93], s[2:3], 2, v[92:93]
	v_lshl_add_u64 v[98:99], v[92:93], 0, v[96:97]
	global_load_dword v103, v[98:99], off
	global_load_dword v104, v[98:99], off offset:128
	global_load_dword v105, v[98:99], off offset:256
	global_load_dword v116, v[98:99], off offset:384
	global_load_dword v93, v[98:99], off offset:512
	global_load_dword v92, v[98:99], off offset:640
	ds_bpermute_b32 v98, v107, v88
	v_cndmask_b32_e64 v121, v229, v230, s[22:23]
	v_readlane_b32 s41, v252, 5
	v_readlane_b32 s42, v252, 6
	v_readlane_b32 s43, v252, 7
	s_waitcnt lgkmcnt(0)
	v_add_f32_e32 v88, v88, v98
	s_nop 1
	v_add_f32_dpp v88, v88, v88 row_ror:8 row_mask:0xf bank_mask:0xf
	s_nop 1
	v_add_f32_dpp v88, v88, v88 row_ror:4 row_mask:0xf bank_mask:0xf
	s_nop 1
	v_add_f32_dpp v88, v88, v88 row_ror:2 row_mask:0xf bank_mask:0xf
	s_nop 1
	v_add_f32_dpp v88, v88, v88 row_ror:1 row_mask:0xf bank_mask:0xf
	v_fmaak_f32 v88, v121, v88, 0x358637bd
	v_mul_f32_e32 v98, 0x4b800000, v88
	v_cmp_gt_f32_e32 vcc, s77, v88
	s_waitcnt vmcnt(13)
	v_lshlrev_b32_e32 v89, 16, v89
	v_cndmask_b32_e32 v88, v88, v98, vcc
	v_rsq_f32_e32 v88, v88
	s_waitcnt vmcnt(12)
	v_lshlrev_b32_e32 v99, 16, v122
	s_waitcnt vmcnt(10)
	v_lshlrev_b32_e32 v100, 16, v102
	v_lshlrev_b32_e32 v101, 16, v123
	v_mul_f32_e32 v98, 0x45800000, v88
	v_cndmask_b32_e32 v102, v88, v98, vcc
	v_mul_f32_e32 v98, v102, v89
	v_mul_f32_e32 v99, v102, v99
	s_and_saveexec_b64 s[18:19], s[26:27]
	s_xor_b64 s[18:19], exec, s[18:19]
	s_cbranch_execz .LBB0_195
	v_bfe_u32 v88, v98, 16, 1
	v_add3_u32 v88, v98, v88, s61
	global_store_short_d16_hi v[60:61], v88, off
	v_bfe_u32 v88, v99, 16, 1
	v_add3_u32 v88, v99, v88, s61
	global_store_short_d16_hi v[62:63], v88, off
	v_mul_f32_e32 v88, v102, v101
	v_bfe_u32 v89, v88, 16, 1
	v_add3_u32 v88, v88, v89, s61
	global_store_short_d16_hi v[64:65], v88, off
	v_mul_f32_e32 v88, v102, v100
	v_bfe_u32 v89, v88, 16, 1
	v_add3_u32 v88, v88, v89, s61
	global_store_short_d16_hi v[66:67], v88, off
.LBB0_195:
	s_or_saveexec_b64 s[18:19], s[18:19]
	v_cndmask_b32_e64 v88, v231, v232, s[22:23]
	v_mov_b32_e32 v89, v97
	v_cndmask_b32_e64 v122, 0, 1, s[10:11]
	v_lshl_add_u64 v[88:89], v[0:1], 0, v[88:89]
	v_cmp_ne_u32_e64 s[28:29], 1, v122
	s_xor_b64 exec, exec, s[18:19]
	s_cbranch_execz .LBB0_199
	s_waitcnt vmcnt(5)
	v_pk_mul_f32 v[100:101], v[102:103], v[100:101] op_sel_hi:[0,1]
	v_pk_mul_f32 v[122:123], v[98:99], v[98:99]
	v_pk_mul_f32 v[124:125], v[100:101], v[100:101]
	v_pk_mul_f32 v[126:127], v[94:95], v[102:103] op_sel_hi:[1,0]
	v_add_f32_e32 v102, v122, v123
	v_cndmask_b32_e64 v95, v95, v127, s[22:23]
	v_cndmask_b32_e64 v94, v94, v126, s[22:23]
	v_add_f32_e32 v102, v125, v102
	v_pk_mul_f32 v[126:127], v[94:95], v[94:95]
	v_add_f32_e32 v102, v124, v102
	v_add_f32_e32 v102, v127, v102
	v_add_f32_e32 v102, v126, v102
	ds_bpermute_b32 v122, v107, v102
	s_waitcnt lgkmcnt(0)
	v_add_f32_e32 v102, v102, v122
	s_nop 1
	v_add_f32_dpp v102, v102, v102 row_ror:8 row_mask:0xf bank_mask:0xf
	s_nop 1
	v_add_f32_dpp v102, v102, v102 row_ror:4 row_mask:0xf bank_mask:0xf
	s_nop 1
	v_add_f32_dpp v102, v102, v102 row_ror:2 row_mask:0xf bank_mask:0xf
	s_nop 1
	v_add_f32_dpp v102, v102, v102 row_ror:1 row_mask:0xf bank_mask:0xf
	v_fmamk_f32 v102, v102, 0x3baaaaab, v206
	v_mul_f32_e32 v122, 0x4b800000, v102
	v_cmp_gt_f32_e32 vcc, s77, v102
	s_nop 1
	v_cndmask_b32_e32 v102, v102, v122, vcc
	v_rsq_f32_e32 v102, v102
	s_nop 0
	v_mul_f32_e32 v122, 0x45800000, v102
	v_cndmask_b32_e32 v102, v102, v122, vcc
	v_pk_mul_f32 v[94:95], v[94:95], v[102:103] op_sel_hi:[1,0]
	s_and_b64 vcc, exec, s[28:29]
	s_waitcnt vmcnt(0)
	v_pk_mul_f32 v[94:95], v[92:93], v[94:95]
	s_cbranch_vccnz .LBB0_198
	ds_bpermute_b32 v123, v107, v95
	ds_bpermute_b32 v122, v107, v94
	s_waitcnt lgkmcnt(0)
	v_pk_mul_f32 v[122:123], v[68:69], v[122:123]
	s_nop 0
	v_cndmask_b32_e64 v123, v123, -v123, s[20:21]
	v_cndmask_b32_e64 v122, v122, -v122, s[20:21]
	v_pk_fma_f32 v[94:95], v[70:71], v[94:95], v[122:123]

; DI float bf2f(bf16_t b) { return __uint_as_float(((unsigned)b) << 16); }
; NI void prepD_row(const P& p, int l, int t0) {
;     ...
;       for (int rr = 0; rr < RBD; ++rr) { float a = 0.f;
; #pragma unroll
;         for (int j = 0; j < 12; ++j) { const float v = bf2f(U[(size_t)(t0 + rr) * INP + O_DCQ + ln + 32 * j]); a += v * v; }
;         ssi[rr] = a; }
;     } else {
; #pragma unroll
;       for (int rr = 0; rr < RBD; ++rr) { float a = 0.f;
; #pragma unroll
;         for (int j = 0; j < 8; ++j) { const float v = bf2f(U[(size_t)(t0 + rr) * INP + O_DCKV + ln + 32 * j]); a += v * v; }
;         ssi[rr] = a; }
;     ...
;     for (int rr = 0; rr < RBD; ++rr) {
;       const int t = t0 + rr;
;       const float rstd_in = rsqrtf(hw_sum(ssi[rr]) * (isq ? (1.f / 384.f) : (1.f / 256.f)) + EPS);
;       if (task < 8) {
.LBB0_199:
	s_or_b64 exec, exec, s[18:19]
	v_lshlrev_b32_e32 v94, 16, v115
	v_fmac_f32_e32 v112, v94, v94
	v_lshlrev_b32_e32 v94, 16, v114
	v_fmac_f32_e32 v112, v94, v94
	v_lshlrev_b32_e32 v94, 16, v113
	v_fmac_f32_e32 v112, v94, v94
	ds_bpermute_b32 v94, v107, v112
	s_and_b64 s[18:19], exec, s[24:25]
	s_waitcnt vmcnt(9)
	v_lshlrev_b32_e32 v101, 16, v120
	s_or_b64 s[16:17], s[18:19], s[16:17]
	s_waitcnt vmcnt(7)
	v_lshlrev_b32_e32 v99, 16, v118
	s_waitcnt lgkmcnt(0)
	v_add_f32_e32 v94, v112, v94
	ds_bpermute_b32 v95, v108, v94
	s_waitcnt vmcnt(6)
	v_lshlrev_b32_e32 v98, 16, v119
	s_waitcnt lgkmcnt(0)
	v_add_f32_e32 v94, v94, v95
	s_nop 1
	v_add_f32_dpp v94, v94, v94 row_ror:4 row_mask:0xf bank_mask:0xf
	s_nop 1
	v_add_f32_dpp v94, v94, v94 row_ror:2 row_mask:0xf bank_mask:0xf
	s_nop 1
	v_add_f32_dpp v94, v94, v94 row_ror:1 row_mask:0xf bank_mask:0xf
	v_fmaak_f32 v94, v121, v94, 0x358637bd
	v_mul_f32_e32 v95, 0x4b800000, v94
	v_cmp_gt_f32_e32 vcc, s77, v94
	s_nop 1
	v_cndmask_b32_e32 v94, v94, v95, vcc
	v_rsq_f32_e32 v94, v94
	v_lshlrev_b32_e32 v95, 16, v117
	v_mul_f32_e32 v100, 0x45800000, v94
	v_cndmask_b32_e32 v100, v94, v100, vcc
	v_mul_f32_e32 v94, v100, v101
	v_mul_f32_e32 v95, v100, v95
	s_and_saveexec_b64 s[18:19], s[26:27]
	s_xor_b64 s[18:19], exec, s[18:19]
	s_cbranch_execnz .LBB0_201
	s_andn2_saveexec_b64 s[18:19], s[18:19]
	s_cbranch_execz .LBB0_182
	s_branch .LBB0_202

; NI void prepD_row(const P& p, int l, int t0) {
;     ...
;       if (task < 8) {
;         const int nsc = isq ? 6 : 4;
; #pragma unroll
;         for (int j = 0; j < 6; ++j) if (j < nsc) x[rr][j] *= rstd_in;
;         float ss = 0.f;
; #pragma unroll
;         for (int j = 0; j < 6; ++j) ss += x[rr][j] * x[rr][j];
;         const float rstd = rsqrtf(hw_sum(ss) * (1.f / 192.f) + EPS);
; #pragma unroll
;         for (int j = 0; j < 6; ++j) x[rr][j] = x[rr][j] * rstd * nwv[j];
;         if (lat) {
;           const int tt = t - NCTX, rpos = tt >> 6, cpos = tt & 63;
;           float sn, c;
;           {
;             sincos_rev((float)rpos * invf, sn, c);
;             const float other = __shfl_xor(x[rr][4], 16);
;             x[rr][4] = (ln < 16) ? (x[rr][4] * c - other * sn) : (other * sn + x[rr][4] * c);
.LBB0_202:
	v_pk_mul_f32 v[98:99], v[100:101], v[98:99] op_sel_hi:[0,1]
	v_pk_mul_f32 v[112:113], v[94:95], v[94:95]
	v_pk_mul_f32 v[100:101], v[90:91], v[100:101] op_sel_hi:[1,0]
	v_pk_mul_f32 v[114:115], v[98:99], v[98:99]
	v_add_f32_e32 v102, v112, v113
	v_cndmask_b32_e64 v91, v91, v101, s[22:23]
	v_cndmask_b32_e64 v90, v90, v100, s[22:23]
	v_add_f32_e32 v102, v115, v102
	v_pk_mul_f32 v[100:101], v[90:91], v[90:91]
	v_add_f32_e32 v102, v114, v102
	v_add_f32_e32 v101, v101, v102
	v_add_f32_e32 v100, v100, v101
	ds_bpermute_b32 v101, v107, v100
	s_waitcnt lgkmcnt(0)
	v_add_f32_e32 v100, v100, v101
	s_nop 1
	v_add_f32_dpp v100, v100, v100 row_ror:8 row_mask:0xf bank_mask:0xf
	s_nop 1
	v_add_f32_dpp v100, v100, v100 row_ror:4 row_mask:0xf bank_mask:0xf
	s_nop 1
	v_add_f32_dpp v100, v100, v100 row_ror:2 row_mask:0xf bank_mask:0xf
	s_nop 1
	v_add_f32_dpp v100, v100, v100 row_ror:1 row_mask:0xf bank_mask:0xf
	v_fmamk_f32 v100, v100, 0x3baaaaab, v206
	v_mul_f32_e32 v101, 0x4b800000, v100
	v_cmp_gt_f32_e32 vcc, s77, v100
	s_nop 1
	v_cndmask_b32_e32 v100, v100, v101, vcc
	v_rsq_f32_e32 v100, v100
	s_nop 0
	v_mul_f32_e32 v101, 0x45800000, v100
	v_cndmask_b32_e32 v100, v100, v101, vcc
	v_pk_mul_f32 v[90:91], v[90:91], v[100:101] op_sel_hi:[1,0]
	s_and_b64 vcc, exec, s[28:29]
	s_waitcnt vmcnt(0)
	v_pk_mul_f32 v[90:91], v[92:93], v[90:91]
	s_cbranch_vccnz .LBB0_181
	ds_bpermute_b32 v93, v107, v91
	ds_bpermute_b32 v92, v107, v90
	s_waitcnt lgkmcnt(0)
	v_pk_mul_f32 v[92:93], v[82:83], v[92:93]
	s_nop 0
	v_cndmask_b32_e64 v93, v93, -v93, s[20:21]
	v_cndmask_b32_e64 v92, v92, -v92, s[20:21]
	v_pk_fma_f32 v[90:91], v[84:85], v[90:91], v[92:93]
	s_branch .LBB0_181

; NI void prepD_row(const P& p, int l, int t0) {
;     ...
;     float nwv[6];
;     const float* nwp = (isq ? p.in[I_MQQK] : p.in[I_MKQK]) + l * 192 + ln;
; #pragma unroll
;     for (int j = 0; j < 6; ++j) nwv[j] = nwp[32 * j];
;     const float invf = exp2f(-(float)(ln & 15) * (13.287712379549449f / 16.f));
; #pragma unroll
;     for (int rr = 0; rr < RBD; ++rr) {
;       const int t = t0 + rr;
;       const float rstd_in = rsqrtf(hw_sum(ssi[rr]) * (isq ? (1.f / 384.f) : (1.f / 256.f)) + EPS);
;       if (task < 8) {
;         const int nsc = isq ? 6 : 4;
; #pragma unroll
;         for (int j = 0; j < 6; ++j) if (j < nsc) x[rr][j] *= rstd_in;
;         float ss = 0.f;
; #pragma unroll
;         for (int j = 0; j < 6; ++j) ss += x[rr][j] * x[rr][j];
;         const float rstd = rsqrtf(hw_sum(ss) * (1.f / 192.f) + EPS);
; #pragma unroll
;         for (int j = 0; j < 6; ++j) x[rr][j] = x[rr][j] * rstd * nwv[j];
;         if (lat) {
;           const int tt = t - NCTX, rpos = tt >> 6, cpos = tt & 63;
;           float sn, c;
;           {
;             sincos_rev((float)rpos * invf, sn, c);
;             const float other = __shfl_xor(x[rr][4], 16);
;             x[rr][4] = (ln < 16) ? (x[rr][4] * c - other * sn) : (other * sn + x[rr][4] * c);
.LBB0_218:
	s_or_b64 exec, exec, s[18:19]
	v_readlane_b32 s36, v252, 4
	v_readlane_b32 s41, v252, 9
	v_readlane_b32 s43, v252, 11
	global_load_ushort v89, v[102:103], off
	global_load_ushort v122, v[102:103], off offset:64
	global_load_ushort v123, v[102:103], off offset:128
	s_nop 0
	global_load_ushort v102, v[102:103], off offset:192
	s_nop 0
	global_load_ushort v120, v[100:101], off
	global_load_ushort v117, v[98:99], off
	global_load_ushort v118, v[92:93], off
	global_load_ushort v119, v[104:105], off
	v_readlane_b32 s40, v252, 8
	v_readlane_b32 s42, v252, 10
	v_mov_b32_e32 v92, s43
	v_mov_b32_e32 v93, s41
	v_cndmask_b32_e64 v93, v92, v93, s[22:23]
	v_mov_b32_e32 v92, s42
	v_mov_b32_e32 v98, s40
	v_cndmask_b32_e64 v92, v92, v98, s[22:23]
	v_lshl_add_u64 v[92:93], s[2:3], 2, v[92:93]
	v_lshl_add_u64 v[98:99], v[92:93], 0, v[96:97]
	global_load_dword v103, v[98:99], off
	global_load_dword v104, v[98:99], off offset:128
	global_load_dword v105, v[98:99], off offset:256
	global_load_dword v116, v[98:99], off offset:384
	global_load_dword v93, v[98:99], off offset:512
	global_load_dword v92, v[98:99], off offset:640
	ds_bpermute_b32 v98, v107, v88
	v_cndmask_b32_e64 v121, v229, v230, s[22:23]
	v_readlane_b32 s37, v252, 5
	v_readlane_b32 s38, v252, 6
	v_readlane_b32 s39, v252, 7
	s_waitcnt lgkmcnt(0)
	v_add_f32_e32 v88, v88, v98
	s_nop 1
	v_add_f32_dpp v88, v88, v88 row_ror:8 row_mask:0xf bank_mask:0xf
	s_nop 1
	v_add_f32_dpp v88, v88, v88 row_ror:4 row_mask:0xf bank_mask:0xf
	s_nop 1
	v_add_f32_dpp v88, v88, v88 row_ror:2 row_mask:0xf bank_mask:0xf
	s_nop 1
	v_add_f32_dpp v88, v88, v88 row_ror:1 row_mask:0xf bank_mask:0xf
	v_fmaak_f32 v88, v121, v88, 0x358637bd
	v_mul_f32_e32 v98, 0x4b800000, v88
	v_cmp_gt_f32_e32 vcc, s77, v88
	s_waitcnt vmcnt(13)
	v_lshlrev_b32_e32 v89, 16, v89
	v_cndmask_b32_e32 v88, v88, v98, vcc
	v_rsq_f32_e32 v88, v88
	s_waitcnt vmcnt(12)
	v_lshlrev_b32_e32 v99, 16, v122
	s_waitcnt vmcnt(10)
	v_lshlrev_b32_e32 v100, 16, v102
	v_lshlrev_b32_e32 v101, 16, v123
	v_mul_f32_e32 v98, 0x45800000, v88
	v_cndmask_b32_e32 v102, v88, v98, vcc
	v_mul_f32_e32 v98, v102, v89
	v_mul_f32_e32 v99, v102, v99
	s_and_saveexec_b64 s[18:19], s[26:27]
	s_xor_b64 s[18:19], exec, s[18:19]
	s_cbranch_execz .LBB0_220
	v_bfe_u32 v88, v98, 16, 1
	v_add3_u32 v88, v98, v88, s61
	global_store_short_d16_hi v[60:61], v88, off
	v_bfe_u32 v88, v99, 16, 1
	v_add3_u32 v88, v99, v88, s61
	global_store_short_d16_hi v[62:63], v88, off
	v_mul_f32_e32 v88, v102, v101
	v_bfe_u32 v89, v88, 16, 1
	v_add3_u32 v88, v88, v89, s61
	global_store_short_d16_hi v[64:65], v88, off
	v_mul_f32_e32 v88, v102, v100
	v_bfe_u32 v89, v88, 16, 1
	v_add3_u32 v88, v88, v89, s61
	global_store_short_d16_hi v[66:67], v88, off

; NI void phase_norm(const P& p, int l, unsigned* ctr, int* s_item, char* lds) {
;     ...
;     for (int rr = 0; rr < 4; ++rr) {
;       const float* xp = xrow_ptr(p, l, t0 + rr) + tid * 8;
;       v0[rr] = *(const float4*)xp; v1[rr] = *(const float4*)(xp + 4);
;     }
;     const float* md = mod + (t0 < NCTX ? 6144 : 0);
;     float wv[8], sc[8], sh[8];
; #pragma unroll
;     for (int i = 0; i < 8; ++i) { const int c0 = tid * 8 + i; wv[i] = nw[c0]; sc[i] = 1.f + md[2048 + c0]; sh[i] = md[c0]; }
; #pragma unroll
;     for (int rr = 0; rr < 4; ++rr) {
;       float ss = v0[rr].x * v0[rr].x + v0[rr].y * v0[rr].y + v0[rr].z * v0[rr].z + v0[rr].w * v0[rr].w +
;                  v1[rr].x * v1[rr].x + v1[rr].y * v1[rr].y + v1[rr].z * v1[rr].z + v1[rr].w * v1[rr].w;
;       ss += __shfl_xor(ss, 32); ss = hw_sum(ss);
;       if ((tid & 63) == 0) red[rr * 4 + (tid >> 6)] = ss;
;     }
.LBB0_510:
	s_lshl_b64 s[0:1], s[0:1], 13
	s_add_u32 s0, s18, s0
	s_addc_u32 s1, s19, s1
	s_cmp_lt_i32 s36, 64
	s_cselect_b32 s74, 0x6000, 0
	v_lshl_add_u64 v[44:45], v[62:63], 0, s[74:75]
	v_lshl_add_u64 v[28:29], v[56:57], 2, s[0:1]
	v_add_co_u32_e32 v30, vcc, s33, v44
	global_load_dwordx4 v[24:27], v[28:29], off offset:16
	global_load_dwordx4 v[36:39], v[28:29], off
	v_lshl_add_u64 v[28:29], v[44:45], 0, s[72:73]
	v_addc_co_u32_e32 v31, vcc, 0, v45, vcc
	global_load_dwordx4 v[52:55], v[30:31], off
	global_load_dwordx4 v[48:51], v[28:29], off offset:16
	s_nop 0
	global_load_dwordx4 v[28:31], v[60:61], off offset:16
	global_load_dwordx4 v[40:43], v[60:61], off
	global_load_dwordx4 v[32:35], v[44:45], off offset:16
	s_nop 0
	global_load_dwordx4 v[44:47], v[44:45], off
	s_waitcnt vmcnt(12)
	v_pk_mul_f32 v[66:67], v[4:5], v[4:5]
	v_pk_mul_f32 v[64:65], v[6:7], v[6:7]
	v_add_f32_e32 v66, v66, v67
	v_add_f32_e32 v64, v66, v64
	v_pk_mul_f32 v[78:79], v[0:1], v[0:1]
	v_add_f32_e32 v64, v64, v65
	v_add_f32_e32 v64, v64, v78
	v_pk_mul_f32 v[76:77], v[2:3], v[2:3]
	v_add_f32_e32 v64, v64, v79
	v_add_f32_e32 v64, v64, v76
	v_add_f32_e32 v64, v64, v77
	ds_bpermute_b32 v65, v68, v64
	s_waitcnt lgkmcnt(0)
	v_add_f32_e32 v64, v64, v65
	ds_bpermute_b32 v65, v69, v64
	s_waitcnt lgkmcnt(0)
	v_add_f32_e32 v64, v64, v65
	s_nop 1
	v_add_f32_dpp v64, v64, v64 row_ror:8 row_mask:0xf bank_mask:0xf
	s_nop 1
	v_add_f32_dpp v64, v64, v64 row_ror:4 row_mask:0xf bank_mask:0xf
	s_nop 1
	v_add_f32_dpp v64, v64, v64 row_ror:2 row_mask:0xf bank_mask:0xf
	ds_bpermute_b32 v65, v73, v64
	s_and_saveexec_b64 s[0:1], s[20:21]
	s_cbranch_execz .LBB0_512
	s_waitcnt lgkmcnt(0)
	v_add_f32_e32 v64, v64, v65
	ds_write_b32 v74, v64
.LBB0_512:
	s_or_b64 exec, exec, s[0:1]
	s_waitcnt vmcnt(10)
	v_pk_mul_f32 v[66:67], v[12:13], v[12:13]
	s_waitcnt lgkmcnt(0)
	v_pk_mul_f32 v[64:65], v[14:15], v[14:15]
	v_add_f32_e32 v66, v66, v67
	v_add_f32_e32 v64, v66, v64
	v_pk_mul_f32 v[78:79], v[8:9], v[8:9]
	v_add_f32_e32 v64, v64, v65
	v_add_f32_e32 v64, v64, v78
	v_pk_mul_f32 v[76:77], v[10:11], v[10:11]
	v_add_f32_e32 v64, v64, v79
	v_add_f32_e32 v64, v64, v76
	v_add_f32_e32 v64, v64, v77
	ds_bpermute_b32 v65, v68, v64
	s_waitcnt lgkmcnt(0)
	v_add_f32_e32 v64, v64, v65
	ds_bpermute_b32 v65, v69, v64
	s_waitcnt lgkmcnt(0)
	v_add_f32_e32 v64, v64, v65
	s_nop 1
	v_add_f32_dpp v64, v64, v64 row_ror:8 row_mask:0xf bank_mask:0xf
	s_nop 1
	v_add_f32_dpp v64, v64, v64 row_ror:4 row_mask:0xf bank_mask:0xf
	s_nop 1
	v_add_f32_dpp v64, v64, v64 row_ror:2 row_mask:0xf bank_mask:0xf
	ds_bpermute_b32 v65, v73, v64
	s_and_saveexec_b64 s[0:1], s[20:21]
	s_cbranch_execz .LBB0_514
	s_waitcnt lgkmcnt(0)
	v_add_f32_e32 v64, v64, v65
	ds_write_b32 v74, v64 offset:16
.LBB0_514:
	s_or_b64 exec, exec, s[0:1]
	s_waitcnt vmcnt(8)
	v_pk_mul_f32 v[66:67], v[20:21], v[20:21]
	s_waitcnt lgkmcnt(0)
	v_pk_mul_f32 v[64:65], v[22:23], v[22:23]
	v_add_f32_e32 v66, v66, v67
	v_add_f32_e32 v64, v66, v64
	v_pk_mul_f32 v[78:79], v[16:17], v[16:17]
	v_add_f32_e32 v64, v64, v65
	v_add_f32_e32 v64, v64, v78
	v_pk_mul_f32 v[76:77], v[18:19], v[18:19]
	v_add_f32_e32 v64, v64, v79
	v_add_f32_e32 v64, v64, v76
	v_add_f32_e32 v64, v64, v77
	ds_bpermute_b32 v65, v68, v64
	s_waitcnt lgkmcnt(0)
	v_add_f32_e32 v64, v64, v65
	ds_bpermute_b32 v65, v69, v64
	s_waitcnt lgkmcnt(0)
	v_add_f32_e32 v64, v64, v65
	s_nop 1
	v_add_f32_dpp v64, v64, v64 row_ror:8 row_mask:0xf bank_mask:0xf
	s_nop 1
	v_add_f32_dpp v64, v64, v64 row_ror:4 row_mask:0xf bank_mask:0xf
	s_nop 1
	v_add_f32_dpp v64, v64, v64 row_ror:2 row_mask:0xf bank_mask:0xf
	ds_bpermute_b32 v65, v73, v64
	s_and_saveexec_b64 s[0:1], s[20:21]
	s_cbranch_execz .LBB0_516
	s_waitcnt lgkmcnt(0)
	v_add_f32_e32 v64, v64, v65
	ds_write_b32 v74, v64 offset:32
.LBB0_516:
	s_or_b64 exec, exec, s[0:1]
	s_waitcnt vmcnt(6)
	v_pk_mul_f32 v[66:67], v[36:37], v[36:37]
	s_waitcnt lgkmcnt(0)
	v_pk_mul_f32 v[64:65], v[38:39], v[38:39]
	v_add_f32_e32 v66, v66, v67
	v_add_f32_e32 v64, v66, v64
	v_pk_mul_f32 v[78:79], v[24:25], v[24:25]
	v_add_f32_e32 v64, v64, v65
	v_add_f32_e32 v64, v64, v78
	v_pk_mul_f32 v[76:77], v[26:27], v[26:27]
	v_add_f32_e32 v64, v64, v79
	v_add_f32_e32 v64, v64, v76
	v_add_f32_e32 v64, v64, v77
	ds_bpermute_b32 v65, v68, v64
	s_waitcnt lgkmcnt(0)
	v_add_f32_e32 v64, v64, v65
	ds_bpermute_b32 v65, v69, v64
	s_waitcnt lgkmcnt(0)
	v_add_f32_e32 v64, v64, v65
	s_nop 1
	v_add_f32_dpp v64, v64, v64 row_ror:8 row_mask:0xf bank_mask:0xf
	s_nop 1
	v_add_f32_dpp v64, v64, v64 row_ror:4 row_mask:0xf bank_mask:0xf
	s_nop 1
	v_add_f32_dpp v64, v64, v64 row_ror:2 row_mask:0xf bank_mask:0xf
	ds_bpermute_b32 v65, v73, v64
	s_and_saveexec_b64 s[0:1], s[20:21]
	s_cbranch_execz .LBB0_477
	s_waitcnt lgkmcnt(0)
	v_add_f32_e32 v64, v64, v65
	ds_write_b32 v74, v64 offset:48
	s_branch .LBB0_477
